# v44 + attention group B: the phase that opens its barrier interval starts with the LDS reads, staging writes before the VALU max chain (segment-head VALU moved back)
# speedup vs baseline: 1.0051x; 1.0051x over previous
; __device__ __forceinline__ void partialSM(f32x16& p0, f32x16& p1, float& m_reg, float& mn, float& alpha) {
;     ...
;   float pmax = p0[0]; for (int r = 1; r < 16; ++r) pmax = fmaxf(pmax, p0[r]); for (int r = 0; r < 16; ++r) pmax = fmaxf(pmax, p1[r]);
;   { auto rr = __builtin_amdgcn_permlane32_swap(__float_as_uint(pmax), __float_as_uint(pmax), false, false);
;     pmax = fmaxf(__uint_as_float(rr[0]), __uint_as_float(rr[1])); }
;   if (__builtin_expect(__all(pmax - m_reg <= THR / SCALE), 1)) { mn = m_reg; alpha = 1.f; }
;   else { mn = fmaxf(m_reg, pmax); alpha = __builtin_amdgcn_exp2f((m_reg - mn) * C); m_reg = mn; }
;   float mnC = -mn * C;
;   for (int r = 0; r < 16; ++r) p0[r] = fmaf(p0[r], C, mnC); for (int r = 0; r < 16; ++r) p1[r] = fmaf(p1[r], C, mnC);
;   for (int r = 0; r < 16; ++r) p0[r] = __builtin_amdgcn_exp2f(p0[r]);
; }
; __device__ __forceinline__ void finishSM(f32x16& p0, f32x16& p1, float alpha, float& l_reg, bf16x8& pa0, bf16x8& pa1, bf16x8& pa2, bf16x8& pa3) {
;   for (int r = 0; r < 16; ++r) p1[r] = __builtin_amdgcn_exp2f(p1[r]);
;   float ps = 0; for (int r = 0; r < 16; ++r) ps += p0[r]; for (int r = 0; r < 16; ++r) ps += p1[r];
;   { auto rr = __builtin_amdgcn_permlane32_swap(__float_as_uint(ps), __float_as_uint(ps), false, false);
;     ps = __uint_as_float(rr[0]) + __uint_as_float(rr[1]); }
;   l_reg = l_reg * alpha + ps;
;     ...
;   PK4(p0, 0, pa0); PK4(p0, 8, pa1); PK4(p1, 0, pa2); PK4(p1, 8, pa3);
;     ...
; }
; __device__ __forceinline__ void qkt(f32x16& p0, f32x16& p1, const char* Kn, const char* Kp, const bf16x8* qr, int r32, int hi) {
;   p0 = f32x16{}; p1 = f32x16{};
; #pragma unroll
;   for (int d0 = 0; d0 < 8; ++d0) { int cb = (d0 * 16 + hi * 8) * 2;
;     bf16x8 b0 = *reinterpret_cast<const bf16x8*>(Kn + KSWZ(r32, cb));
;     bf16x8 b1 = *reinterpret_cast<const bf16x8*>(Kn + KSWZ(32 + r32, cb));
;     p0 = __builtin_amdgcn_mfma_f32_32x32x16_bf16(b0, qr[d0], p0, 0, 0, 0);
;     p1 = __builtin_amdgcn_mfma_f32_32x32x16_bf16(b1, qr[d0], p1, 0, 0, 0); }
; #pragma unroll
;   for (int d1 = 0; d1 < 4; ++d1) { int cb = (d1 * 16 + hi * 8) * 2;
;     bf16x8 b0 = *reinterpret_cast<const bf16x8*>(Kp + KPSWZ(r32, cb));
;     bf16x8 b1 = *reinterpret_cast<const bf16x8*>(Kp + KPSWZ(32 + r32, cb));
;     p0 = __builtin_amdgcn_mfma_f32_32x32x16_bf16(b0, qr[8 + d1], p0, 0, 0, 0);
;     p1 = __builtin_amdgcn_mfma_f32_32x32x16_bf16(b1, qr[8 + d1], p1, 0, 0, 0); }
.Lpp_loop:
	s_barrier
	ds_read_b128 v[192:195], v160 offset:16384
	ds_read_b128 v[196:199], v160 offset:24576
	ds_read_b128 v[200:203], v161 offset:16384
	ds_read_b128 v[204:207], v161 offset:24576
	ds_read_b128 v[208:211], v162 offset:16384
	ds_read_b128 v[212:215], v162 offset:24576
	ds_read_b128 v[216:219], v163 offset:16384
	ds_read_b128 v[220:223], v163 offset:24576
	s_waitcnt vmcnt(0)
	ds_write_b128 v246, v[232:235]
	ds_write_b128 v246, v[236:239] offset:8192
	ds_write_b128 v248, v[240:243]
	ds_write_b128 v244, v[224:227]
	ds_write_b128 v244, v[228:231] offset:8192
	v_max3_f32 v250, v80, v81, v82
	v_max3_f32 v250, v250, v83, v84
	v_max3_f32 v250, v250, v85, v86
	v_max3_f32 v250, v250, v87, v88
	v_max3_f32 v250, v250, v89, v90
	v_max3_f32 v250, v250, v91, v92
	v_max3_f32 v250, v250, v93, v94
	v_max3_f32 v250, v250, v95, v64
	v_max3_f32 v250, v250, v65, v66
	v_max3_f32 v250, v250, v67, v68
	v_max3_f32 v250, v250, v69, v70
	v_max3_f32 v250, v250, v71, v72
	v_max3_f32 v250, v250, v73, v74
	v_max3_f32 v250, v250, v75, v76
	v_max3_f32 v250, v250, v77, v78
	v_max3_f32 v250, v250, v79, v79
	v_cmp_lt_f32_e64 vcc, s64, |v250|
	global_load_dwordx4 v[232:235], v180, s[50:51]
	global_load_dwordx4 v[236:239], v180, s[52:53]
	global_load_dwordx4 v[224:227], v180, s[54:55] offset:256
	global_load_dwordx4 v[228:231], v180, s[56:57] offset:256
	global_load_dwordx4 v[240:243], v181, s[58:59]
	s_cmp_lg_u32 s62, 0
	s_cbranch_scc1 .Lpp_safe_Ba
	s_cbranch_vccnz .Lpp_sw_Ba
	v_exp_f32_e32 v80, v80
	v_exp_f32_e32 v81, v81
	v_exp_f32_e32 v82, v82
	v_exp_f32_e32 v83, v83
	v_exp_f32_e32 v84, v84
	v_exp_f32_e32 v85, v85
	v_exp_f32_e32 v86, v86
	v_exp_f32_e32 v87, v87
	v_exp_f32_e32 v88, v88
	v_exp_f32_e32 v89, v89
	v_exp_f32_e32 v90, v90
	v_exp_f32_e32 v91, v91
	v_exp_f32_e32 v92, v92
	v_exp_f32_e32 v93, v93
	v_exp_f32_e32 v94, v94
	v_exp_f32_e32 v95, v95
	v_exp_f32_e32 v64, v64
	v_exp_f32_e32 v65, v65
	v_exp_f32_e32 v66, v66
	v_exp_f32_e32 v67, v67
	v_exp_f32_e32 v68, v68
	v_exp_f32_e32 v69, v69
	v_exp_f32_e32 v70, v70
	v_exp_f32_e32 v71, v71
	v_exp_f32_e32 v72, v72
	v_exp_f32_e32 v73, v73
	v_exp_f32_e32 v74, v74
	v_exp_f32_e32 v75, v75
	v_exp_f32_e32 v76, v76
	v_exp_f32_e32 v77, v77
	v_exp_f32_e32 v78, v78
	v_exp_f32_e32 v79, v79
	v_add_f32_e32 v249, v80, v81
	v_add_f32_e32 v250, v82, v83
	v_add_f32_e32 v251, v84, v85
	v_add_f32_e32 v182, v86, v87
	v_add_f32_e32 v249, v88, v249
	v_add_f32_e32 v250, v89, v250
	v_add_f32_e32 v251, v90, v251
	v_add_f32_e32 v182, v91, v182
	v_add_f32_e32 v249, v92, v249
	v_add_f32_e32 v250, v93, v250
	v_add_f32_e32 v251, v94, v251
	v_add_f32_e32 v182, v95, v182
	v_add_f32_e32 v249, v64, v249
	v_add_f32_e32 v250, v65, v250
	v_add_f32_e32 v251, v66, v251
	v_add_f32_e32 v182, v67, v182
	v_add_f32_e32 v249, v68, v249
	v_add_f32_e32 v250, v69, v250
	v_add_f32_e32 v251, v70, v251
	v_add_f32_e32 v182, v71, v182
	v_add_f32_e32 v249, v72, v249
	v_add_f32_e32 v250, v73, v250
	v_add_f32_e32 v251, v74, v251
	v_add_f32_e32 v182, v75, v182
	v_add_f32_e32 v249, v76, v249
	v_add_f32_e32 v250, v77, v250
	v_add_f32_e32 v251, v78, v251
	v_add_f32_e32 v182, v79, v182
	v_add_f32_e32 v249, v249, v250
	v_add_f32_e32 v251, v251, v182
	v_add_f32_e32 v249, v249, v251
	v_add_f32_e32 v176, v176, v249
	v_cvt_pk_bf16_f32 v144, v80, v81
	v_cvt_pk_bf16_f32 v145, v82, v83
	v_cvt_pk_bf16_f32 v146, v84, v85
	v_cvt_pk_bf16_f32 v147, v86, v87
	v_cvt_pk_bf16_f32 v148, v88, v89
	v_cvt_pk_bf16_f32 v149, v90, v91
	v_cvt_pk_bf16_f32 v150, v92, v93
	v_cvt_pk_bf16_f32 v151, v94, v95
	v_cvt_pk_bf16_f32 v152, v64, v65
	v_cvt_pk_bf16_f32 v153, v66, v67
	v_cvt_pk_bf16_f32 v154, v68, v69
	v_cvt_pk_bf16_f32 v155, v70, v71
	v_cvt_pk_bf16_f32 v156, v72, v73
	v_cvt_pk_bf16_f32 v157, v74, v75
	v_cvt_pk_bf16_f32 v158, v76, v77
	v_cvt_pk_bf16_f32 v159, v78, v79
.Lpp_send_Ba:
	s_add_i32 s11, s11, 1
	s_waitcnt lgkmcnt(6)
	v_mfma_f32_32x32x16_bf16 v[80:95], v[192:195], v[136:139], 0
	v_mfma_f32_32x32x16_bf16 v[64:79], v[196:199], v[136:139], 0
	s_add_i32 s36, s35, 2
	s_min_u32 s36, s36, 67
	s_lshl_b32 s44, s36, 6
	ds_read_b128 v[192:195], v164 offset:16384
	ds_read_b128 v[196:199], v164 offset:24576
	s_waitcnt lgkmcnt(6)
	v_mfma_f32_32x32x16_bf16 v[80:95], v[200:203], v[132:135], v[80:95]
	v_mfma_f32_32x32x16_bf16 v[64:79], v[204:207], v[132:135], v[64:79]
	s_add_i32 s45, s31, s44
	s_add_i32 s46, s24, s44
	s_add_i32 s46, s46, 0xffffff00
	ds_read_b128 v[200:203], v165 offset:16384
	ds_read_b128 v[204:207], v165 offset:24576
	s_waitcnt lgkmcnt(6)
	v_mfma_f32_32x32x16_bf16 v[80:95], v[208:211], v[128:131], v[80:95]
	v_mfma_f32_32x32x16_bf16 v[64:79], v[212:215], v[128:131], v[64:79]
	s_cmp_lt_u32 s36, 4
	s_cselect_b32 s36, s45, s46
	s_add_i32 s37, s35, 1
	ds_read_b128 v[208:211], v166 offset:16384
	ds_read_b128 v[212:215], v166 offset:24576
	s_waitcnt lgkmcnt(6)
	v_mfma_f32_32x32x16_bf16 v[80:95], v[216:219], v[124:127], v[80:95]
	v_mfma_f32_32x32x16_bf16 v[64:79], v[220:223], v[124:127], v[64:79]
	s_min_u32 s37, s37, 67
	s_lshl_b32 s44, s37, 6
	s_add_i32 s45, s31, s44
	ds_read_b128 v[216:219], v167 offset:16384
	ds_read_b128 v[220:223], v167 offset:24576
	s_waitcnt lgkmcnt(6)
	v_mfma_f32_32x32x16_bf16 v[80:95], v[192:195], v[120:123], v[80:95]
	v_mfma_f32_32x32x16_bf16 v[64:79], v[196:199], v[120:123], v[64:79]
	s_add_i32 s46, s24, s44
	s_add_i32 s46, s46, 0xffffff00
	s_cmp_lt_u32 s37, 4
	ds_read_b128 v[192:195], v168 offset:8192
	ds_read_b128 v[196:199], v168 offset:12288
	s_waitcnt lgkmcnt(6)
	v_mfma_f32_32x32x16_bf16 v[80:95], v[200:203], v[140:143], v[80:95]
	v_mfma_f32_32x32x16_bf16 v[64:79], v[204:207], v[140:143], v[64:79]
	s_cselect_b32 s37, s45, s46
	s_add_i32 s35, s35, 1
	s_lshl_b32 s44, s36, 12
	ds_read_b128 v[200:203], v169 offset:8192
	ds_read_b128 v[204:207], v169 offset:12288
	s_waitcnt lgkmcnt(6)
; __device__ __forceinline__ void qkt(f32x16& p0, f32x16& p1, const char* Kn, const char* Kp, const bf16x8* qr, int r32, int hi) {
;   p0 = f32x16{}; p1 = f32x16{};
; #pragma unroll
;   for (int d0 = 0; d0 < 8; ++d0) { int cb = (d0 * 16 + hi * 8) * 2;
;     bf16x8 b0 = *reinterpret_cast<const bf16x8*>(Kn + KSWZ(r32, cb));
;     bf16x8 b1 = *reinterpret_cast<const bf16x8*>(Kn + KSWZ(32 + r32, cb));
;     p0 = __builtin_amdgcn_mfma_f32_32x32x16_bf16(b0, qr[d0], p0, 0, 0, 0);
;     p1 = __builtin_amdgcn_mfma_f32_32x32x16_bf16(b1, qr[d0], p1, 0, 0, 0); }
; #pragma unroll
;   for (int d1 = 0; d1 < 4; ++d1) { int cb = (d1 * 16 + hi * 8) * 2;
;     bf16x8 b0 = *reinterpret_cast<const bf16x8*>(Kp + KPSWZ(r32, cb));
;     bf16x8 b1 = *reinterpret_cast<const bf16x8*>(Kp + KPSWZ(32 + r32, cb));
;     p0 = __builtin_amdgcn_mfma_f32_32x32x16_bf16(b0, qr[8 + d1], p0, 0, 0, 0);
;     p1 = __builtin_amdgcn_mfma_f32_32x32x16_bf16(b1, qr[8 + d1], p1, 0, 0, 0); }
; }
; __device__ __forceinline__ int v_st(int k, int c) { const int kk = (k & ~0xC) | ((k & 4) << 1) | ((k & 8) >> 1); return ((kk >> 3) * 4 + (c >> 5)) * 512 + ((kk & 7) * 32 + (c & 31)) * 2; }
; __device__ __forceinline__ int v_rd_base(int lane) { return ((lane & 3) << 3) | (((lane >> 2) & 3) << 6) | (((lane >> 4) & 1) << 5) | (((lane >> 5) & 1) << 8); }
; template <int OFF> __device__ __forceinline__ s16x4 tr_read(int vb) {
;   s16x4 r; asm volatile("ds_read_b64_tr_b16 %0, %1 offset:%2" : "=&v"(r) : "v"(vb), "i"(OFF) : "memory"); return r;
; }
; template <int D0> __device__ __forceinline__ void pv_one(f32x16& od, int vb, bf16x8 pa0, bf16x8 pa1, bf16x8 pa2, bf16x8 pa3) {
;   const s16x4 l0 = tr_read<v_rd_off(D0, 0, 0)>(vb), h0 = tr_read<v_rd_off(D0, 0, 1)>(vb), l1 = tr_read<v_rd_off(D0, 1, 0)>(vb), h1 = tr_read<v_rd_off(D0, 1, 1)>(vb);
;   const s16x4 l2 = tr_read<v_rd_off(D0, 2, 0)>(vb), h2 = tr_read<v_rd_off(D0, 2, 1)>(vb), l3 = tr_read<v_rd_off(D0, 3, 0)>(vb), h3 = tr_read<v_rd_off(D0, 3, 1)>(vb);
;   asm volatile("s_waitcnt lgkmcnt(0)" ::: "memory"); SBAR();
;     ...
;   od = __builtin_amdgcn_mfma_f32_32x32x16_bf16(pa0, PK(l0, h0), od, 0, 0, 0);
;   od = __builtin_amdgcn_mfma_f32_32x32x16_bf16(pa1, PK(l1, h1), od, 0, 0, 0);
;   od = __builtin_amdgcn_mfma_f32_32x32x16_bf16(pa2, PK(l2, h2), od, 0, 0, 0);
;   od = __builtin_amdgcn_mfma_f32_32x32x16_bf16(pa3, PK(l3, h3), od, 0, 0, 0);
;     ...
; }
	v_mfma_f32_32x32x16_bf16 v[80:95], v[208:211], v[116:119], v[80:95]
	v_mfma_f32_32x32x16_bf16 v[64:79], v[212:215], v[116:119], v[64:79]
	s_add_u32 s50, s47, s44
	s_addc_u32 s51, s63, 0
	s_add_u32 s52, s50, 0x20000
	ds_read_b128 v[208:211], v170 offset:8192
	ds_read_b128 v[212:215], v170 offset:12288
	s_waitcnt lgkmcnt(6)
	v_mfma_f32_32x32x16_bf16 v[80:95], v[216:219], v[112:115], v[80:95]
	v_mfma_f32_32x32x16_bf16 v[64:79], v[220:223], v[112:115], v[64:79]
	s_addc_u32 s53, s51, 0
	s_lshl_b32 s44, s37, 12
	s_add_u32 s54, s47, s44
	ds_read_b128 v[216:219], v171 offset:8192
	ds_read_b128 v[220:223], v171 offset:12288
	s_waitcnt lgkmcnt(6)
	v_mfma_f32_32x32x16_bf16 v[80:95], v[192:195], v[108:111], v[80:95]
	v_mfma_f32_32x32x16_bf16 v[64:79], v[196:199], v[108:111], v[64:79]
	s_addc_u32 s55, s63, 0
	s_add_u32 s56, s54, 0x20000
	s_addc_u32 s57, s55, 0
	ds_read_b64_tr_b16 v[192:193], v174 offset:0
	ds_read_b64_tr_b16 v[194:195], v174 offset:2048
	ds_read_b64_tr_b16 v[196:197], v174 offset:4096
	ds_read_b64_tr_b16 v[198:199], v174 offset:6144
	s_waitcnt lgkmcnt(8)
	v_mfma_f32_32x32x16_bf16 v[80:95], v[200:203], v[104:107], v[80:95]
	v_mfma_f32_32x32x16_bf16 v[64:79], v[204:207], v[104:107], v[64:79]
	s_lshl_b32 s44, s36, 10
	s_add_u32 s58, s60, s44
	s_addc_u32 s59, s61, 0
	ds_read_b64_tr_b16 v[200:201], v174 offset:8192
	ds_read_b64_tr_b16 v[202:203], v174 offset:10240
	ds_read_b64_tr_b16 v[204:205], v174 offset:12288
	ds_read_b64_tr_b16 v[206:207], v174 offset:14336
	s_waitcnt lgkmcnt(10)
	v_mfma_f32_32x32x16_bf16 v[80:95], v[208:211], v[100:103], v[80:95]
	v_mfma_f32_32x32x16_bf16 v[64:79], v[212:215], v[100:103], v[64:79]
	ds_read_b64_tr_b16 v[208:209], v174 offset:512
	ds_read_b64_tr_b16 v[210:211], v174 offset:2560
	ds_read_b64_tr_b16 v[212:213], v174 offset:4608
	ds_read_b64_tr_b16 v[214:215], v174 offset:6656
	s_waitcnt lgkmcnt(12)
	v_mfma_f32_32x32x16_bf16 v[80:95], v[216:219], v[96:99], v[80:95]
	v_mfma_f32_32x32x16_bf16 v[64:79], v[220:223], v[96:99], v[64:79]
	ds_read_b64_tr_b16 v[216:217], v174 offset:8704
	ds_read_b64_tr_b16 v[218:219], v174 offset:10752
	ds_read_b64_tr_b16 v[220:221], v174 offset:12800
	ds_read_b64_tr_b16 v[222:223], v174 offset:14848
	s_waitcnt lgkmcnt(12)
	v_mfma_f32_32x32x16_bf16 v[0:15], v[144:147], v[192:195], v[0:15]
	ds_read_b64_tr_b16 v[192:193], v174 offset:1024
	ds_read_b64_tr_b16 v[194:195], v174 offset:3072
	v_mfma_f32_32x32x16_bf16 v[0:15], v[148:151], v[196:199], v[0:15]
	ds_read_b64_tr_b16 v[196:197], v174 offset:5120
	ds_read_b64_tr_b16 v[198:199], v174 offset:7168
	s_waitcnt lgkmcnt(12)
	v_mfma_f32_32x32x16_bf16 v[0:15], v[152:155], v[200:203], v[0:15]
	ds_read_b64_tr_b16 v[200:201], v174 offset:9216
	ds_read_b64_tr_b16 v[202:203], v174 offset:11264
	v_mfma_f32_32x32x16_bf16 v[0:15], v[156:159], v[204:207], v[0:15]
	ds_read_b64_tr_b16 v[204:205], v174 offset:13312
	ds_read_b64_tr_b16 v[206:207], v174 offset:15360
	s_waitcnt lgkmcnt(12)
	v_mfma_f32_32x32x16_bf16 v[48:63], v[144:147], v[208:211], v[48:63]
	ds_read_b64_tr_b16 v[208:209], v174 offset:1536
	ds_read_b64_tr_b16 v[210:211], v174 offset:3584
	v_mfma_f32_32x32x16_bf16 v[48:63], v[148:151], v[212:215], v[48:63]
	ds_read_b64_tr_b16 v[212:213], v174 offset:5632
	ds_read_b64_tr_b16 v[214:215], v174 offset:7680
	s_waitcnt lgkmcnt(12)
	v_mfma_f32_32x32x16_bf16 v[48:63], v[152:155], v[216:219], v[48:63]
	ds_read_b64_tr_b16 v[216:217], v174 offset:9728
	ds_read_b64_tr_b16 v[218:219], v174 offset:11776
	v_mfma_f32_32x32x16_bf16 v[48:63], v[156:159], v[220:223], v[48:63]
	ds_read_b64_tr_b16 v[220:221], v174 offset:13824
	ds_read_b64_tr_b16 v[222:223], v174 offset:15872
	s_waitcnt lgkmcnt(12)
	v_mfma_f32_32x32x16_bf16 v[32:47], v[144:147], v[192:195], v[32:47]
	v_mfma_f32_32x32x16_bf16 v[32:47], v[148:151], v[196:199], v[32:47]
	s_waitcnt lgkmcnt(8)
	v_mfma_f32_32x32x16_bf16 v[32:47], v[152:155], v[200:203], v[32:47]
	v_mfma_f32_32x32x16_bf16 v[32:47], v[156:159], v[204:207], v[32:47]
	s_waitcnt lgkmcnt(4)
	v_mfma_f32_32x32x16_bf16 v[16:31], v[144:147], v[208:211], v[16:31]
	v_mfma_f32_32x32x16_bf16 v[16:31], v[148:151], v[212:215], v[16:31]
	s_waitcnt lgkmcnt(0)
	v_mfma_f32_32x32x16_bf16 v[16:31], v[152:155], v[216:219], v[16:31]
	v_mfma_f32_32x32x16_bf16 v[16:31], v[156:159], v[220:223], v[16:31]
	s_barrier
; __device__ __forceinline__ void partialSM(f32x16& p0, f32x16& p1, float& m_reg, float& mn, float& alpha) {
;     ...
;   float pmax = p0[0]; for (int r = 1; r < 16; ++r) pmax = fmaxf(pmax, p0[r]); for (int r = 0; r < 16; ++r) pmax = fmaxf(pmax, p1[r]);
;   { auto rr = __builtin_amdgcn_permlane32_swap(__float_as_uint(pmax), __float_as_uint(pmax), false, false);
;     pmax = fmaxf(__uint_as_float(rr[0]), __uint_as_float(rr[1])); }
;   if (__builtin_expect(__all(pmax - m_reg <= THR / SCALE), 1)) { mn = m_reg; alpha = 1.f; }
;   else { mn = fmaxf(m_reg, pmax); alpha = __builtin_amdgcn_exp2f((m_reg - mn) * C); m_reg = mn; }
;   float mnC = -mn * C;
;   for (int r = 0; r < 16; ++r) p0[r] = fmaf(p0[r], C, mnC); for (int r = 0; r < 16; ++r) p1[r] = fmaf(p1[r], C, mnC);
;   for (int r = 0; r < 16; ++r) p0[r] = __builtin_amdgcn_exp2f(p0[r]);
; }
; __device__ __forceinline__ void finishSM(f32x16& p0, f32x16& p1, float alpha, float& l_reg, bf16x8& pa0, bf16x8& pa1, bf16x8& pa2, bf16x8& pa3) {
;   for (int r = 0; r < 16; ++r) p1[r] = __builtin_amdgcn_exp2f(p1[r]);
;   float ps = 0; for (int r = 0; r < 16; ++r) ps += p0[r]; for (int r = 0; r < 16; ++r) ps += p1[r];
;   { auto rr = __builtin_amdgcn_permlane32_swap(__float_as_uint(ps), __float_as_uint(ps), false, false);
;     ps = __uint_as_float(rr[0]) + __uint_as_float(rr[1]); }
;   l_reg = l_reg * alpha + ps;
;     ...
;   PK4(p0, 0, pa0); PK4(p0, 8, pa1); PK4(p1, 0, pa2); PK4(p1, 8, pa3);
	ds_read_b128 v[192:195], v160
	ds_read_b128 v[196:199], v160 offset:8192
	ds_read_b128 v[200:203], v161
	ds_read_b128 v[204:207], v161 offset:8192
	ds_read_b128 v[208:211], v162
	ds_read_b128 v[212:215], v162 offset:8192
	ds_read_b128 v[216:219], v163
	ds_read_b128 v[220:223], v163 offset:8192
	s_waitcnt vmcnt(0)
	ds_write_b128 v247, v[232:235]
	ds_write_b128 v247, v[236:239] offset:8192
	ds_write_b128 v183, v[240:243]
	ds_write_b128 v245, v[224:227]
	ds_write_b128 v245, v[228:231] offset:8192
	v_max3_f32 v250, v80, v81, v82
	v_max3_f32 v250, v250, v83, v84
	v_max3_f32 v250, v250, v85, v86
	v_max3_f32 v250, v250, v87, v88
	v_max3_f32 v250, v250, v89, v90
	v_max3_f32 v250, v250, v91, v92
	v_max3_f32 v250, v250, v93, v94
	v_max3_f32 v250, v250, v95, v64
	v_max3_f32 v250, v250, v65, v66
	v_max3_f32 v250, v250, v67, v68
	v_max3_f32 v250, v250, v69, v70
	v_max3_f32 v250, v250, v71, v72
	v_max3_f32 v250, v250, v73, v74
	v_max3_f32 v250, v250, v75, v76
	v_max3_f32 v250, v250, v77, v78
	v_max3_f32 v250, v250, v79, v79
	v_cmp_lt_f32_e64 vcc, s64, |v250|
	global_load_dwordx4 v[232:235], v180, s[50:51]
	global_load_dwordx4 v[236:239], v180, s[52:53]
	global_load_dwordx4 v[224:227], v180, s[54:55] offset:256
	global_load_dwordx4 v[228:231], v180, s[56:57] offset:256
	global_load_dwordx4 v[240:243], v181, s[58:59]
	s_cmp_lg_u32 s62, 0
	s_cbranch_scc1 .Lpp_safe_Bb
	s_cbranch_vccnz .Lpp_sw_Bb
	v_exp_f32_e32 v80, v80
	v_exp_f32_e32 v81, v81
	v_exp_f32_e32 v82, v82
	v_exp_f32_e32 v83, v83
	v_exp_f32_e32 v84, v84
	v_exp_f32_e32 v85, v85
	v_exp_f32_e32 v86, v86
	v_exp_f32_e32 v87, v87
	v_exp_f32_e32 v88, v88
	v_exp_f32_e32 v89, v89
	v_exp_f32_e32 v90, v90
	v_exp_f32_e32 v91, v91
	v_exp_f32_e32 v92, v92
	v_exp_f32_e32 v93, v93
	v_exp_f32_e32 v94, v94
	v_exp_f32_e32 v95, v95
	v_exp_f32_e32 v64, v64
	v_exp_f32_e32 v65, v65
	v_exp_f32_e32 v66, v66
	v_exp_f32_e32 v67, v67
	v_exp_f32_e32 v68, v68
	v_exp_f32_e32 v69, v69
	v_exp_f32_e32 v70, v70
	v_exp_f32_e32 v71, v71
	v_exp_f32_e32 v72, v72
	v_exp_f32_e32 v73, v73
	v_exp_f32_e32 v74, v74
	v_exp_f32_e32 v75, v75
	v_exp_f32_e32 v76, v76
	v_exp_f32_e32 v77, v77
	v_exp_f32_e32 v78, v78
	v_exp_f32_e32 v79, v79
	v_add_f32_e32 v249, v80, v81
	v_add_f32_e32 v250, v82, v83
	v_add_f32_e32 v251, v84, v85
	v_add_f32_e32 v182, v86, v87
	v_add_f32_e32 v249, v88, v249
	v_add_f32_e32 v250, v89, v250
	v_add_f32_e32 v251, v90, v251
	v_add_f32_e32 v182, v91, v182
	v_add_f32_e32 v249, v92, v249
	v_add_f32_e32 v250, v93, v250
	v_add_f32_e32 v251, v94, v251
	v_add_f32_e32 v182, v95, v182
	v_add_f32_e32 v249, v64, v249
	v_add_f32_e32 v250, v65, v250
	v_add_f32_e32 v251, v66, v251
	v_add_f32_e32 v182, v67, v182
	v_add_f32_e32 v249, v68, v249
	v_add_f32_e32 v250, v69, v250
	v_add_f32_e32 v251, v70, v251
	v_add_f32_e32 v182, v71, v182
	v_add_f32_e32 v249, v72, v249
	v_add_f32_e32 v250, v73, v250
	v_add_f32_e32 v251, v74, v251
	v_add_f32_e32 v182, v75, v182
	v_add_f32_e32 v249, v76, v249
	v_add_f32_e32 v250, v77, v250
	v_add_f32_e32 v251, v78, v251
	v_add_f32_e32 v182, v79, v182
	v_add_f32_e32 v249, v249, v250
	v_add_f32_e32 v251, v251, v182
	v_add_f32_e32 v249, v249, v251
	v_add_f32_e32 v176, v176, v249
	v_cvt_pk_bf16_f32 v144, v80, v81
	v_cvt_pk_bf16_f32 v145, v82, v83
	v_cvt_pk_bf16_f32 v146, v84, v85
	v_cvt_pk_bf16_f32 v147, v86, v87
	v_cvt_pk_bf16_f32 v148, v88, v89
	v_cvt_pk_bf16_f32 v149, v90, v91
	v_cvt_pk_bf16_f32 v150, v92, v93
	v_cvt_pk_bf16_f32 v151, v94, v95
	v_cvt_pk_bf16_f32 v152, v64, v65
	v_cvt_pk_bf16_f32 v153, v66, v67
	v_cvt_pk_bf16_f32 v154, v68, v69
	v_cvt_pk_bf16_f32 v155, v70, v71
	v_cvt_pk_bf16_f32 v156, v72, v73
	v_cvt_pk_bf16_f32 v157, v74, v75
	v_cvt_pk_bf16_f32 v158, v76, v77
	v_cvt_pk_bf16_f32 v159, v78, v79
